# GQA/SWA in-proj: the workgroup's second tile (last before the grid barrier) stores q/k/v write-through (duplicated epilogue), first tile stays write-back
# speedup vs baseline: 1.0029x; 1.0029x over previous
.LBB0_424:
	s_cmp_eq_u32 s39, 4
	s_cbranch_scc1 .LBB0_979
	s_cmp_eq_u32 s39, 0
	s_cselect_b64 s[22:23], -1, 0
	s_cmp_gt_i32 s74, 2
	s_cselect_b64 s[4:5], -1, 0
	s_and_b64 s[4:5], s[22:23], s[4:5]
	v_mbcnt_lo_u32_b32 v187, -1, 0
	v_mbcnt_hi_u32_b32 v187, -1, v187
	s_and_b64 vcc, exec, s[4:5]
	v_and_b32_e32 v189, 15, v187
	v_ashrrev_i32_e32 v191, 4, v187
	s_cbranch_vccnz .LBB0_972
	s_cmp_eq_u32 s39, 3
	s_cselect_b64 s[4:5], -1, 0
	s_cmp_gt_i32 s74, 5
	s_cselect_b64 s[6:7], -1, 0
	s_and_b64 s[4:5], s[4:5], s[6:7]
	s_andn2_b64 vcc, exec, s[4:5]
	s_mov_b64 s[4:5], -1
	s_cbranch_vccz .LBB0_972
	s_cmp_lt_i32 s39, 2
	s_cbranch_scc1 .LBB0_687
	s_cmp_gt_i32 s39, 2
	s_cbranch_scc0 .LBB0_639
	s_cmp_lg_u32 s62, 0
	s_cbranch_scc1 .Lq3w_entry
	s_load_dwordx2 s[4:5], s[0:1], 0xd0
	v_readlane_b32 s48, v254, 36
	v_readlane_b32 s49, v254, 45
	v_readlane_b32 s50, v255, 17
	v_readlane_b32 s96, v255, 32
	v_readlane_b32 s97, v255, 33
	v_lshlrev_b32_e32 v131, 7, v189
	v_lshl_add_u32 v131, v191, 4, v131
	v_add_u32_e32 v132, 0x20000, v131
	v_lshlrev_b32_e32 v133, 5, v191
	v_and_b32_e32 v180, 3, v187
	v_lshlrev_b32_e32 v180, 4, v180
	v_lshrrev_b32_e32 v136, 2, v187
	v_add_lshl_u32 v180, v180, v136, 2
	s_lshl_b32 s51, s48, 8
	s_add_u32 s51, s51, s49
	s_sub_u32 s58, s48, 32
	s_and_b32 s59, s58, 3
	s_lshl_b32 s59, s59, 8
	s_add_u32 s59, s59, s49
	s_cmp_gt_u32 s74, 3
	s_cbranch_scc1 .Lq3_kv
	s_lshl_b32 s35, s51, 11
	s_lshl_b32 s70, s74, 9
	s_add_u32 s35, s35, s70
	s_lshl_b32 s70, s19, 1
	s_add_u32 s35, s35, s70
	s_add_u32 s35, s35, 0x3c00000
	s_mov_b32 s33, 0x8000
	s_mov_b32 s34, 0x28000
	s_mov_b32 s36, 0x3e38aa3b
	s_mov_b32 s71, 0xa0
	v_lshrrev_b32_e32 v130, 2, v187
	v_lshlrev_b32_e32 v130, 11, v130
	s_mov_b64 s[24:25], 0
	s_branch .Lq3_common

.Lq3w_entry:
	s_load_dwordx2 s[4:5], s[0:1], 0xd0
	v_readlane_b32 s48, v254, 36
	v_readlane_b32 s49, v254, 45
	v_readlane_b32 s50, v255, 17
	v_readlane_b32 s96, v255, 32
	v_readlane_b32 s97, v255, 33
	v_lshlrev_b32_e32 v131, 7, v189
	v_lshl_add_u32 v131, v191, 4, v131
	v_add_u32_e32 v132, 0x20000, v131
	v_lshlrev_b32_e32 v133, 5, v191
	v_and_b32_e32 v180, 3, v187
	v_lshlrev_b32_e32 v180, 4, v180
	v_lshrrev_b32_e32 v136, 2, v187
	v_add_lshl_u32 v180, v180, v136, 2
	s_lshl_b32 s51, s48, 8
	s_add_u32 s51, s51, s49
	s_sub_u32 s58, s48, 32
	s_and_b32 s59, s58, 3
	s_lshl_b32 s59, s59, 8
	s_add_u32 s59, s59, s49
	s_cmp_gt_u32 s74, 3
	s_cbranch_scc1 .Lq3w_kv
	s_lshl_b32 s35, s51, 11
	s_lshl_b32 s70, s74, 9
	s_add_u32 s35, s35, s70
	s_lshl_b32 s70, s19, 1
	s_add_u32 s35, s35, s70
	s_add_u32 s35, s35, 0x3c00000
	s_mov_b32 s33, 0x8000
	s_mov_b32 s34, 0x28000
	s_mov_b32 s36, 0x3e38aa3b
	s_mov_b32 s71, 0xa0
	v_lshrrev_b32_e32 v130, 2, v187
	v_lshlrev_b32_e32 v130, 11, v130
	s_mov_b64 s[24:25], 0
	s_branch .Lq3w_common
